# weight-prep phase: waves that get a fifth transpose item rotated away from the waves that get the fifth norm iteration; otherwise as v91
# speedup vs baseline: 1.0007x; 1.0007x over previous
; __global__ void __launch_bounds__(NTHR, 2) mk_fwd(Args args) {
;     ...
;                 float* scr = (float*)lds + wid * (64 * 33);
;                 constexpr int I0 = 184 * 16, I1 = I0 + 24 * 4, I2 = I1 + 32 * 4, I3 = I2 + 3 * 32 * 8, I4 = I3 + 32 * 16, I5 = I4 + 176 * 16, I6 = I5 + 32 * 44;
;                 for (int it = gw; it < I6; it += NGW) {
;                     if (it < I0) transpose_item(ap->in[I_WIN] + (size_t)l * 1024 * IN_DIM, 1024, IN_DIM, (bf16_t*)(ws + O_WIN), 1024, it, MAT_IN, nullptr, scr, lane);
;                     else if (it < I1) transpose_item(ap->in[I_WUQ] + (size_t)l * 256 * 768, 256, 768, (bf16_t*)(ws + O_WUQ), 256, it - I0, MAT_UQ, ap->in[I_QNORM] + l * 256, scr, lane);
;                     else if (it < I2) transpose_item(ap->in[I_WUKV] + (size_t)l * 128 * 1024, 128, 1024, (bf16_t*)(ws + O_WUKV), 256, it - I1, MAT_PLAIN, ap->in[I_KVNORM] + l * 128, scr, lane);
;                     else if (it < I3) { const int r = it - I2, br = r / 256; const float* src = (br == 0 ? ap->in[I_WBRA] : (br == 1 ? ap->in[I_WBRB] : ap->in[I_WBRC])) + (size_t)l * 512 * 1024;
;                         transpose_item(src, 512, 1024, (bf16_t*)(ws + O_WBR) + (size_t)br * 1024 * 512, 512, r - br * 256, MAT_PLAIN, nullptr, scr, lane); }
;                     else if (it < I4) transpose_item(ap->in[I_WOUT] + (size_t)l * 1024 * 1024, 1024, 1024, (bf16_t*)(ws + O_WOUT), 1024, it - I3, MAT_PLAIN, nullptr, scr, lane);
;                     else if (it < I5) transpose_item(ap->in[I_WUP] + (size_t)l * 1024 * FF2, 1024, FF2, (bf16_t*)(ws + O_WUP), 1024, it - I4, MAT_PLAIN, nullptr, scr, lane);
;                     else transpose_item(ap->in[I_WDOWN] + (size_t)l * FF * 1024, FF, 1024, (bf16_t*)(ws + O_WDOWN), FF, it - I5, MAT_PLAIN, nullptr, scr, lane);
;                 }
.LBB0_1609:
	s_and_b64 vcc, exec, s[0:1]
	s_cbranch_vccz .LBB0_2220
	v_readlane_b32 s0, v254, 33
	s_cmp_eq_u32 s0, 0
	s_cbranch_scc0 .LBB0_2220
	v_readlane_b32 s0, v254, 21
	s_mov_b32 s37, s29
	s_cmpk_gt_i32 s0, 0x21df
	v_lshlrev_b32_e32 v0, 3, v202
	v_lshlrev_b32_e32 v2, 4, v202
	v_readlane_b32 s1, v254, 22
	s_cbranch_scc1 .LBB0_2170
	v_readlane_b32 s0, v254, 20
	s_mulk_i32 s0, 0x2100
	v_and_b32_e32 v1, 31, v200
	v_lshrrev_b32_e32 v3, 5, v202
	s_add_i32 s2, s0, 0
	v_readlane_b32 s0, v254, 27
	v_mul_u32_u24_e32 v4, 0x84, v3
	v_lshlrev_b32_e32 v5, 2, v1
	v_and_b32_e32 v16, 56, v0
	v_readlane_b32 s1, v254, 28
	v_add3_u32 v24, s2, v4, v5
	v_lshrrev_b32_e32 v25, 3, v202
	v_lshlrev_b32_e32 v4, 1, v16
	v_mov_b32_e32 v5, v36
	s_mov_b32 s18, s0
	s_ashr_i32 s19, s0, 31
	v_mul_u32_u24_e32 v6, 0x84, v16
	v_lshl_add_u64 v[14:15], s[4:5], 0, v[4:5]
	s_mov_b64 s[0:1], 0x6320000
	v_lshlrev_b32_e32 v7, 2, v25
	s_mov_b64 s[16:17], 0x52a0000
	v_lshl_add_u64 v[4:5], v[14:15], 0, s[0:1]
	v_add3_u32 v26, s2, v6, v7
	s_mov_b64 s[0:1], 0x5820000
	s_lshl_b64 s[2:3], s[18:19], 22
	s_lshl_b64 s[10:11], s[18:19], 21
	v_lshl_add_u64 v[10:11], v[14:15], 0, s[16:17]
	s_mov_b32 s16, s18
	v_lshl_add_u64 v[6:7], v[14:15], 0, s[0:1]
	s_mov_b64 s[0:1], 0x5620000
	s_add_u32 s13, s4, 0x5320000
	v_writelane_b32 v254, s16, 27
	v_lshl_add_u64 v[8:9], v[14:15], 0, s[0:1]
	s_addc_u32 s26, s5, 0
	s_lshl_b32 s0, s18, 7
	v_writelane_b32 v254, s17, 28
	s_mov_b64 s[16:17], 0x5240000
	s_lshl_b64 s[14:15], s[18:19], 19
	s_ashr_i32 s1, s0, 31
	s_lshl_b32 s18, s18, 8
	v_lshl_add_u64 v[12:13], v[14:15], 0, s[16:17]
	s_mov_b64 s[16:17], 0x46c0000
	s_ashr_i32 s19, s18, 31
	v_lshlrev_b32_e32 v17, 5, v202
	v_lshl_add_u64 v[14:15], v[14:15], 0, s[16:17]
	s_lshl_b64 s[16:17], s[0:1], 2
	v_readlane_b32 s0, v254, 21
	v_or_b32_e32 v27, 8, v25
	v_or_b32_e32 v28, 16, v25
	v_or_b32_e32 v29, 24, v25
	v_and_or_b32 v30, v2, 16, v233
	v_and_b32_e32 v31, 32, v17
	v_lshlrev_b32_e32 v16, 1, v16
	s_lshl_b64 s[28:29], s[18:19], 2
	s_add_i32 s27, s0, 0x400
	s_and_b32 s27, s27, 0x7ff
	v_readlane_b32 s1, v254, 22
	s_branch .LBB0_1615
